# down-projection skinny int8 GEMM (sample rows): 7 K-blocks / 21 loads in flight per trip instead of two full-latency waits per block; on top of v21
# speedup vs baseline: 1.0054x; 1.0054x over previous
.LBB0_1110:
	s_cmp_lt_u32 s6, 7
	s_cbranch_scc1 .Lski8_tail_0
	v_add_co_u32_e32 v34, vcc, 0x2b000, v18
	s_nop 1
	v_addc_co_u32_e32 v35, vcc, 0, v19, vcc
	global_load_dwordx4 v[50:53], v[18:19], off
	global_load_dwordx4 v[54:57], v[16:17], off
	global_load_dwordx4 v[58:61], v[34:35], off
	global_load_dwordx4 v[62:65], v[18:19], off offset:64
	global_load_dwordx4 v[66:69], v[16:17], off offset:64
	global_load_dwordx4 v[70:73], v[34:35], off offset:64
	global_load_dwordx4 v[98:101], v[18:19], off offset:128
	global_load_dwordx4 v[178:181], v[16:17], off offset:128
	global_load_dwordx4 v[182:185], v[34:35], off offset:128
	global_load_dwordx4 v[186:189], v[18:19], off offset:192
	global_load_dwordx4 v[190:193], v[16:17], off offset:192
	global_load_dwordx4 v[194:197], v[34:35], off offset:192
	global_load_dwordx4 v[198:201], v[18:19], off offset:256
	global_load_dwordx4 v[202:205], v[16:17], off offset:256
	global_load_dwordx4 v[206:209], v[34:35], off offset:256
	global_load_dwordx4 v[210:213], v[18:19], off offset:320
	global_load_dwordx4 v[214:217], v[16:17], off offset:320
	global_load_dwordx4 v[218:221], v[34:35], off offset:320
	global_load_dwordx4 v[222:225], v[18:19], off offset:384
	global_load_dwordx4 v[226:229], v[16:17], off offset:384
	global_load_dwordx4 v[230:233], v[34:35], off offset:384
	s_mov_b64 s[98:99], 0x1c0
	v_lshl_add_u64 v[16:17], v[16:17], 0, s[98:99]
	v_lshl_add_u64 v[18:19], v[18:19], 0, s[98:99]
	s_add_i32 s6, s6, -7
	s_waitcnt vmcnt(18)
	v_mfma_i32_16x16x64_i8 v[6:9], v[50:53], v[54:57], v[6:9]
	v_mfma_i32_16x16x64_i8 v[2:5], v[58:61], v[54:57], v[2:5]
	s_waitcnt vmcnt(15)
	v_mfma_i32_16x16x64_i8 v[6:9], v[62:65], v[66:69], v[6:9]
	v_mfma_i32_16x16x64_i8 v[2:5], v[70:73], v[66:69], v[2:5]
	s_waitcnt vmcnt(12)
	v_mfma_i32_16x16x64_i8 v[6:9], v[98:101], v[178:181], v[6:9]
	v_mfma_i32_16x16x64_i8 v[2:5], v[182:185], v[178:181], v[2:5]
	s_waitcnt vmcnt(9)
	v_mfma_i32_16x16x64_i8 v[6:9], v[186:189], v[190:193], v[6:9]
	v_mfma_i32_16x16x64_i8 v[2:5], v[194:197], v[190:193], v[2:5]
	s_waitcnt vmcnt(6)
	v_mfma_i32_16x16x64_i8 v[6:9], v[198:201], v[202:205], v[6:9]
	v_mfma_i32_16x16x64_i8 v[2:5], v[206:209], v[202:205], v[2:5]
	s_waitcnt vmcnt(3)
	v_mfma_i32_16x16x64_i8 v[6:9], v[210:213], v[214:217], v[6:9]
	v_mfma_i32_16x16x64_i8 v[2:5], v[218:221], v[214:217], v[2:5]
	s_waitcnt vmcnt(0)
	v_mfma_i32_16x16x64_i8 v[6:9], v[222:225], v[226:229], v[6:9]
	v_mfma_i32_16x16x64_i8 v[2:5], v[230:233], v[226:229], v[2:5]
	s_branch .LBB0_1110
.Lski8_tail_0:
	s_cmp_eq_u32 s6, 0
	s_cbranch_scc1 .Lski8_done_0

.Lski8_done_0:
	s_nop 3
	v_cvt_f32_i32_e32 v6, v6
	v_cvt_f32_i32_e32 v7, v7
	v_cvt_f32_i32_e32 v8, v8
	v_cvt_f32_i32_e32 v9, v9
	v_cvt_f32_i32_e32 v2, v2
	v_cvt_f32_i32_e32 v3, v3
	v_cvt_f32_i32_e32 v4, v4
	v_cvt_f32_i32_e32 v5, v5
	ds_write2_b32 v24, v6, v7 offset1:16
	ds_write2_b32 v24, v8, v9 offset0:32 offset1:48
	ds_write2_b32 v25, v2, v3 offset1:16
	ds_write2_b32 v25, v4, v5 offset0:32 offset1:48
	s_waitcnt lgkmcnt(0)
	s_barrier
	s_and_saveexec_b64 s[6:7], s[0:1]
	s_cbranch_execz .LBB0_1114
	ds_read_b32 v2, v22
	s_mov_b64 s[10:11], 0
	v_mov_b32_e32 v5, v22
	v_mov_b32_e32 v4, v21
